# attention: hoist loop-invariant q_gain loads out of chunk loop; keep Q prefetch and O stores in flight (vmcnt fixes)
# baseline (speedup 1.0000x reference)
; #define LAS __attribute__((address_space(3)))
; __device__ __forceinline__ void attn_phase(int wave_s, LAS unsigned char* lds, const bf16* QKV, bf16* O, const float* qg, const float* kg, const float* sinks, const float* bt) {
;     ...
;     const int tid = tid_, lane = tid & 63, r32 = lane & 31, hi = lane >> 5, wid = __builtin_amdgcn_readfirstlane(tid >> 6);
;     LAS bf16* Ks = (LAS bf16*)(lds + ALDS_K); LAS bf16* Vt = (LAS bf16*)(lds + ALDS_V); LAS float* Bs = (LAS float*)(lds + ALDS_B);
;     float gq = 0.f, gk = 0.f;
;     for (int d = 0; d < HD; ++d) { gq = fmaxf(gq, fabsf(qg[d])); gk = fmaxf(gk, fabsf(kg[d])); }
;     const float shift = 8.0f * gq * gk;
;     for (int unit = blockIdx.x; unit < BATCH * 64 * NKV; unit += gridDim.x) {
;         const int kvh = unit & 3, nb = (unit >> 2) & 63, b = unit >> 8;
;         __syncthreads();
;         const long rowbase = (long)b * SEQ + (long)(nb - 1) * 128;
; #pragma unroll
;         for (int i = 0; i < 4; ++i) { int tq = tid; asm volatile("" : "+v"(tq)); const int p = tq + NTHR * i, jrow = p >> 3, ch = p & 7; const bool ok = (nb > 0) || (jrow >= 128);
;             v4u kw = (v4u){0u, 0u, 0u, 0u}, vw = (v4u){0u, 0u, 0u, 0u};
;             if (ok) { const bf16* src = QKV + (size_t)(rowbase + jrow) * NQKV + NH * HD + kvh * HD + ch * 8; kw = *(const v4u*)src; vw = *(const v4u*)(src + NKV * HD); }
;             float kf[8] = {bflo(kw.x), bfhi(kw.x), bflo(kw.y), bfhi(kw.y), bflo(kw.z), bfhi(kw.z), bflo(kw.w), bfhi(kw.w)};
;             float s = 0.f;
; #pragma unroll
;             for (int e = 0; e < 8; ++e) s += kf[e] * kf[e];
;             s = sum8(s);
;             const float rs = __builtin_amdgcn_rsqf(s * (1.0f / 64.0f) + EPS);
;             const f32x4 g0 = *(const f32x4*)(kg + ch * 8), g1 = *(const f32x4*)(kg + ch * 8 + 4);
;             v4u ko; ko.x = pk2(kf[0] * rs * g0.x, kf[1] * rs * g0.y); ko.y = pk2(kf[2] * rs * g0.z, kf[3] * rs * g0.w); ko.z = pk2(kf[4] * rs * g1.x, kf[5] * rs * g1.y); ko.w = pk2(kf[6] * rs * g1.z, kf[7] * rs * g1.w);
;             *(LAS v4u*)(Ks + jrow * KS_STRIDE + ch * 8) = ko;
;             LAS bf16* vd = Vt + (ch * 8) * VT_STRIDE + jrow;
;             vd[0 * VT_STRIDE] = (bf16)(vw.x & 0xffffu); vd[1 * VT_STRIDE] = (bf16)(vw.x >> 16); vd[2 * VT_STRIDE] = (bf16)(vw.y & 0xffffu); vd[3 * VT_STRIDE] = (bf16)(vw.y >> 16);
.LBB0_472:
	s_add_u32 s16, s12, s10
	s_addc_u32 s17, s13, s11
	global_load_dwordx4 v[4:7], v0, s[16:17] offset:16
	global_load_dwordx4 v[8:11], v0, s[16:17]
	s_add_u32 s16, s14, s10
	s_addc_u32 s17, s15, s11
	global_load_dwordx4 v[12:15], v0, s[16:17]
	global_load_dwordx4 v[16:19], v0, s[16:17] offset:16
	s_add_u32 s10, s10, 32
	s_addc_u32 s11, s11, 0
	s_cmpk_eq_i32 s10, 0x100
	s_waitcnt vmcnt(2)
	v_max3_f32 v3, v3, |v8|, |v9|
	v_max3_f32 v3, v3, |v10|, |v11|
	s_waitcnt vmcnt(1)
	v_max3_f32 v2, v2, |v12|, |v13|
	v_max3_f32 v2, v2, |v14|, |v15|
	v_max3_f32 v3, v3, |v4|, |v5|
	s_waitcnt vmcnt(0)
	v_max3_f32 v2, v2, |v16|, |v17|
	v_max3_f32 v3, v3, |v6|, |v7|
	v_max3_f32 v2, v2, |v18|, |v19|
	s_cbranch_scc0 .LBB0_472
	v_readlane_b32 s10, v255, 3
	v_or_b32_e32 v142, s55, v1
	v_readlane_b32 s11, v255, 4
	s_andn2_b64 vcc, exec, s[10:11]
	v_readfirstlane_b32 s23, v142
	s_cbranch_vccnz .LBB0_534
	s_add_u32 s20, s8, 0x1200000
	s_addc_u32 s21, s9, 0
	s_ashr_i32 s16, s23, 6
	s_add_u32 s26, s8, 0x18400000
	s_addc_u32 s27, s9, 0
	s_lshl_b32 s50, s92, 6
	s_lshl_b64 s[10:11], s[50:51], 2
	s_add_u32 s4, s4, s10
	s_addc_u32 s5, s5, s11
	s_add_u32 s28, s6, s10
	s_addc_u32 s29, s7, s11
	s_lshl_b32 s50, s92, 5
	s_lshl_b64 s[6:7], s[50:51], 2
	s_add_u32 s17, s2, s6
	s_movk_i32 s2, 0x600
	v_mul_f32_e32 v3, 0x41000000, v3
	v_bfe_u32 v6, v1, 5, 1
	v_cmp_gt_i32_e64 s[14:15], s2, v142
	s_mul_i32 s2, s16, 0x300
	v_mul_f32_e32 v143, v2, v3
	s_addc_u32 s22, s3, s7
	v_and_b32_e32 v128, 31, v1
	s_add_i32 s2, s2, 0
	v_lshlrev_b32_e32 v2, 2, v6
	v_and_b32_e32 v4, 32, v1
	v_mov_b32_e32 v5, v0
	s_lshl_b32 s3, s16, 12
	s_add_i32 s2, s2, 0x11200
	v_sub_u32_e32 v2, v128, v2
	v_lshl_add_u64 v[130:131], s[4:5], 0, v[4:5]
	s_add_i32 s3, s3, 0
	v_lshlrev_b32_e32 v4, 4, v1
	v_lshl_add_u32 v145, v2, 2, s2
	s_lshl_b32 s2, s16, 7
	s_add_i32 s3, s3, 0x14000
	v_and_b32_e32 v4, 0x70, v4
	v_and_b32_e32 v3, 63, v1
	s_add_i32 s2, s2, 0
	v_add_u32_e32 v148, s3, v4
	v_lshrrev_b32_e32 v4, 1, v1
	s_add_i32 s2, s2, 0x12a00
	v_cmp_gt_u32_e64 s[4:5], 32, v3
	v_lshlrev_b32_e32 v3, 4, v6
	v_and_b32_e32 v4, 16, v4
	v_lshl_add_u32 v146, v128, 2, s2
	v_add_u32_e32 v147, s2, v3
	v_lshl_add_u32 v7, v128, 1, s3
	v_bfe_u32 v8, v1, 3, 3
	v_lshl_add_u64 v[4:5], s[8:9], 0, v[4:5]
	s_mov_b64 s[2:3], 0x18428040
	v_and_b32_e32 v1, 7, v1
	v_lshlrev_b32_e32 v149, 7, v8
	v_lshl_add_u64 v[132:133], v[4:5], 0, s[2:3]
	v_mul_u32_u24_e32 v4, 0x90, v128
	v_lshlrev_b32_e32 v1, 4, v1
	v_lshlrev_b32_e32 v2, 3, v6
	v_mul_u32_u24_e32 v9, 0x208, v128
	v_lshlrev_b32_e32 v6, 9, v6
	v_or_b32_e32 v10, 0x400, v149
	v_or_b32_e32 v11, 0x800, v149
	v_or_b32_e32 v12, 0xc00, v149
	v_add3_u32 v150, v4, v3, 0
	s_add_i32 s2, 0, 0x9000
	v_lshl_or_b32 v4, v8, 12, v1
	v_mov_b32_e32 v5, v0
	v_readlane_b32 s35, v255, 0
	v_mul_f32_e32 v144, 0x3fb8aa3b, v143
	v_mov_b32_e32 v129, v0
	s_andn2_b32 s23, s23, 63
	v_add3_u32 v151, v9, v2, s2
	v_lshl_add_u64 v[134:135], s[8:9], 0, v[4:5]
	v_lshlrev_b32_e32 v136, 1, v2
	v_add_u32_e32 v152, v7, v6
	v_add_u32_e32 v153, v148, v10
	v_add_u32_e32 v154, v148, v11
	v_add_u32_e32 v155, v148, v12
	s_mov_b32 s34, s35
	global_load_dwordx4 v[164:167], v[130:131], off offset:16
	global_load_dwordx4 v[168:171], v[130:131], off
	global_load_dwordx4 v[172:175], v[130:131], off offset:80
	global_load_dwordx4 v[176:179], v[130:131], off offset:64
	global_load_dwordx4 v[180:183], v[130:131], off offset:144
	global_load_dwordx4 v[184:187], v[130:131], off offset:128
	global_load_dwordx4 v[188:191], v[130:131], off offset:208
	global_load_dwordx4 v[192:195], v[130:131], off offset:192
	s_branch .LBB0_476

; #define LAS __attribute__((address_space(3)))
; #define LDS_WAIT() asm volatile("s_waitcnt lgkmcnt(0)" ::: "memory")
; __device__ __forceinline__ unsigned pk2(float lo, float hi) { f32x2_t v = {lo, hi}; bf16x2_t b = __builtin_convertvector(v, bf16x2_t); return __builtin_bit_cast(unsigned, b); }
; __device__ __forceinline__ void attn_phase(int wave_s, LAS unsigned char* lds, const bf16* QKV, bf16* O, const float* qg, const float* kg, const float* sinks, const float* bt) {
;     ...
;         __syncthreads();
;         const int h = kvh * 8 + wid; const float sink2 = (sinks[h] - shift) * LOG2E;
;         const LAS float* Bh = Bs + wid * 192 + (r32 - 4 * hi);
;         LAS float* wsf = (LAS float*)(lds + ALDS_END) + wid * 32;
;         const bf16* Qb = QKV + ((size_t)b * SEQ + nb * 128 + r32) * NQKV + h * HD + hi * 8;
;         v4u qw[4];
; #pragma unroll
;         for (int d0 = 0; d0 < 4; ++d0) qw[d0] = *(const v4u*)(Qb + d0 * 16);
;     ...
;                         for (int db = 0; db < 2; ++db) { const LAS bf16* vp = Vt + (db * 32 + r32) * VT_STRIDE + 32 * (c + kk) + 16 * ks + 4 * hi;
;                             const v2u lo = *(const LAS v2u*)vp, hh = *(const LAS v2u*)(vp + 8); const v4u vv = (v4u){lo.x, lo.y, hh.x, hh.y};
;                             o[db] = __builtin_amdgcn_mfma_f32_32x32x16_bf16(pa, __builtin_bit_cast(bf16x8, vv), o[db], 0, 0, 0); } } } }
;             LDS_WAIT();
;             LAS bf16* stg = (LAS bf16*)(lds + ALDS_OST) + wid * 2048;
; #pragma unroll
;             for (int rq = 0; rq < 4; ++rq) { const f32x4 iv = *(const LAS f32x4*)(wsf + 8 * rq + 4 * hi);
; #pragma unroll
;                 for (int e = 0; e < 4; ++e) { const int r = 4 * rq + e, q = 8 * rq + 4 * hi + e; stg[q * 64 + r32] = (bf16)(pk2(o[0][r] * iv[e], 0.f) & 0xffffu); stg[q * 64 + 32 + r32] = (bf16)(pk2(o[1][r] * iv[e], 0.f) & 0xffffu); } }
;             LDS_WAIT();
;             bf16* Ow = O + ((size_t)b * SEQ + nb * 128 + 32 * c) * DM + h * HD;
; #pragma unroll
;             for (int i = 0; i < 4; ++i) { const int row = i * 8 + (lane >> 3), ch = lane & 7; const v4u v = *(const LAS v4u*)(stg + row * 64 + ch * 8); *(v4u*)(Ow + (size_t)row * DM + ch * 8) = v; }
.LBB0_497:
	s_or_b64 exec, exec, s[2:3]
	s_lshr_b32 s2, s35, 2
	s_and_b32 s10, s2, 63
	s_lshl_b32 s37, s10, 7
	s_lshl_b32 s2, s36, 9
	s_lshl_b32 s36, s10, 19
	s_lshl_b32 s10, s31, 3
	s_add_i32 s2, s23, s2
	s_add_i32 s10, s10, s16
	s_ashr_i32 s3, s2, 31
	s_ashr_i32 s11, s10, 31
	s_lshl_b64 s[2:3], s[2:3], 1
	s_lshl_b64 s[12:13], s[10:11], 2
	s_add_u32 s12, s17, s12
	s_addc_u32 s13, s22, s13
	s_lshl_b32 s11, s30, 7
	s_or_b32 s11, s8, s11
	v_or_b32_e32 v4, s11, v128
	v_mov_b64_e32 v[2:3], s[26:27]
	s_waitcnt lgkmcnt(0)
	s_barrier
	global_load_dword v1, v0, s[12:13]
	v_mad_u64_u32 v[2:3], s[12:13], v4, s70, v[2:3]
	v_mov_b32_e32 v4, 0x1400
	s_lshl_b32 s10, s10, 6
	v_mad_i32_i24 v3, s9, v4, v3
	s_ashr_i32 s11, s10, 31
	v_lshl_add_u64 v[2:3], s[10:11], 1, v[2:3]
	v_mov_b32_e32 v137, v0
	v_lshl_add_u64 v[2:3], v[2:3], 0, v[136:137]
	global_load_dwordx4 v[96:99], v[2:3], off
	global_load_dwordx4 v[100:103], v[2:3], off offset:32
	global_load_dwordx4 v[104:107], v[2:3], off offset:64
	global_load_dwordx4 v[108:111], v[2:3], off offset:96
	s_add_u32 s8, s37, s8
	s_addc_u32 s9, 0, s9
	s_lshl_b64 s[6:7], s[6:7], 25
	v_mov_b64_e32 v[2:3], s[2:3]
	v_lshl_add_u64 v[4:5], s[8:9], 0, v[128:129]
	s_or_b32 s6, s6, s36
	v_mad_u64_u32 v[2:3], s[8:9], v4, s70, v[2:3]
	s_add_u32 s2, s6, s2
	v_mad_i32_i24 v3, v5, s70, v3
	s_addc_u32 s3, s7, s3
	v_lshl_add_u64 v[138:139], v[132:133], 0, v[2:3]
	v_lshl_add_u64 v[140:141], v[134:135], 0, s[2:3]
	s_mov_b32 s36, 0
	s_mov_b64 s[90:91], 0
	v_mov_b32_e32 v156, v151
	v_mov_b32_e32 v157, v150
	s_waitcnt vmcnt(4)
	v_sub_f32_e32 v1, v1, v143
	v_mul_f32_e32 v1, 0x3fb8aa3b, v1
	v_exp_f32_e32 v137, v1
	s_waitcnt vmcnt(0)
	s_branch .LBB0_499
.LBB0_498:
	v_cvt_pk_bf16_f32 v18, v121, v122
	v_cvt_pk_bf16_f32 v19, v123, v124
	v_cvt_pk_bf16_f32 v20, v125, v126
	v_cvt_pk_bf16_f32 v21, v127, v158
	ds_read2_b64 v[22:25], v156 offset0:32 offset1:34
	ds_read2_b64 v[26:29], v156 offset0:36 offset1:38
	s_waitcnt lgkmcnt(1)
	v_mfma_f32_32x32x16_bf16 v[2:17], v[18:21], v[22:25], v[2:17]
	ds_read2_b64 v[22:25], v120 offset0:64 offset1:66
	s_mov_b32 s2, 0x1d400000
	v_add_u32_e32 v157, 0x1200, v157
	v_add_u32_e32 v156, 64, v156
	s_waitcnt lgkmcnt(0)
	v_mfma_f32_32x32x16_bf16 v[80:95], v[18:21], v[22:25], v[80:95]
	v_cvt_pk_bf16_f32 v18, v117, v119
	v_cvt_pk_bf16_f32 v19, v112, v113
	v_cvt_pk_bf16_f32 v20, v114, v115
	v_cvt_pk_bf16_f32 v21, v116, v118
	ds_read2_b64 v[22:25], v120 offset0:68 offset1:70
	s_waitcnt lgkmcnt(0)
	s_nop 0
	v_mfma_f32_32x32x16_bf16 v[2:17], v[18:21], v[26:29], v[2:17]
	s_waitcnt lgkmcnt(0)
	v_mfma_f32_32x32x16_bf16 v[80:95], v[18:21], v[22:25], v[80:95]
	ds_read_b128 v[18:21], v147
	s_waitcnt lgkmcnt(0)
	s_nop 7
	v_mul_f32_e32 v1, v2, v18
	v_cvt_pk_bf16_f32 v1, v1, s0
	ds_write_b16 v152, v1
	v_mul_f32_e32 v1, v80, v18
	v_cvt_pk_bf16_f32 v1, v1, s0
	ds_write_b16 v152, v1 offset:64
	v_mul_f32_e32 v1, v3, v19
	v_cvt_pk_bf16_f32 v1, v1, s0
	ds_write_b16 v152, v1 offset:128
	v_mul_f32_e32 v1, v81, v19
	v_cvt_pk_bf16_f32 v1, v1, s0
	ds_write_b16 v152, v1 offset:192
	v_mul_f32_e32 v1, v4, v20
	v_cvt_pk_bf16_f32 v1, v1, s0
	ds_write_b16 v152, v1 offset:256
	v_mul_f32_e32 v1, v82, v20
	v_cvt_pk_bf16_f32 v1, v1, s0
	ds_write_b16 v152, v1 offset:320
	v_mul_f32_e32 v1, v5, v21
	v_cvt_pk_bf16_f32 v1, v1, s0
	ds_write_b16 v152, v1 offset:384
	v_mul_f32_e32 v1, v83, v21
	v_cvt_pk_bf16_f32 v1, v1, s0
	ds_write_b16 v152, v1 offset:448
	ds_read_b128 v[2:5], v147 offset:32
	s_waitcnt lgkmcnt(0)
	v_mul_f32_e32 v1, v6, v2
	v_cvt_pk_bf16_f32 v1, v1, s0
	ds_write_b16 v152, v1 offset:1024
	v_mul_f32_e32 v1, v84, v2
	v_cvt_pk_bf16_f32 v1, v1, s0
	ds_write_b16 v152, v1 offset:1088
	v_mul_f32_e32 v1, v7, v3
	v_cvt_pk_bf16_f32 v1, v1, s0
	ds_write_b16 v152, v1 offset:1152
	v_mul_f32_e32 v1, v85, v3
	v_cvt_pk_bf16_f32 v1, v1, s0
	ds_write_b16 v152, v1 offset:1216
	v_mul_f32_e32 v1, v8, v4
	v_cvt_pk_bf16_f32 v1, v1, s0
	ds_write_b16 v152, v1 offset:1280
	v_mul_f32_e32 v1, v86, v4
	v_cvt_pk_bf16_f32 v1, v1, s0
	ds_write_b16 v152, v1 offset:1344
	v_mul_f32_e32 v1, v9, v5
	v_cvt_pk_bf16_f32 v1, v1, s0
	ds_write_b16 v152, v1 offset:1408
	v_mul_f32_e32 v1, v87, v5
	v_cvt_pk_bf16_f32 v1, v1, s0
	ds_write_b16 v152, v1 offset:1472
	ds_read_b128 v[2:5], v147 offset:64
	v_lshl_add_u64 v[6:7], v[140:141], 0, s[90:91]
	v_add_co_u32_e32 v8, vcc, s2, v6
	s_mov_b32 s2, 0x1d408000
	s_waitcnt lgkmcnt(0)
	v_mul_f32_e32 v1, v10, v2
	v_cvt_pk_bf16_f32 v1, v1, s0
	ds_write_b16 v152, v1 offset:2048
	v_mul_f32_e32 v1, v88, v2
	v_cvt_pk_bf16_f32 v1, v1, s0
	ds_write_b16 v152, v1 offset:2112
	v_mul_f32_e32 v1, v11, v3
	v_cvt_pk_bf16_f32 v1, v1, s0
	ds_write_b16 v152, v1 offset:2176
	v_mul_f32_e32 v1, v89, v3
	v_cvt_pk_bf16_f32 v1, v1, s0
	ds_write_b16 v152, v1 offset:2240
	v_mul_f32_e32 v1, v12, v4
	v_cvt_pk_bf16_f32 v1, v1, s0
	ds_write_b16 v152, v1 offset:2304
	v_mul_f32_e32 v1, v90, v4
	v_cvt_pk_bf16_f32 v1, v1, s0
	ds_write_b16 v152, v1 offset:2368
	v_mul_f32_e32 v1, v13, v5
	v_cvt_pk_bf16_f32 v1, v1, s0
	ds_write_b16 v152, v1 offset:2432
	v_mul_f32_e32 v1, v91, v5
	v_cvt_pk_bf16_f32 v1, v1, s0
	ds_write_b16 v152, v1 offset:2496
	ds_read_b128 v[2:5], v147 offset:96
	v_addc_co_u32_e32 v9, vcc, 0, v7, vcc
	s_add_u32 s90, s90, 0x20000
	s_addc_u32 s91, s91, 0
	s_waitcnt lgkmcnt(0)
	v_mul_f32_e32 v1, v14, v2
	v_cvt_pk_bf16_f32 v1, v1, s0
	ds_write_b16 v152, v1 offset:3072
	v_mul_f32_e32 v1, v92, v2
	v_cvt_pk_bf16_f32 v1, v1, s0
	ds_write_b16 v152, v1 offset:3136
	v_mul_f32_e32 v1, v15, v3
	v_cvt_pk_bf16_f32 v1, v1, s0
	ds_write_b16 v152, v1 offset:3200
	v_mul_f32_e32 v1, v93, v3
	v_cvt_pk_bf16_f32 v1, v1, s0
	ds_write_b16 v152, v1 offset:3264
	v_mul_f32_e32 v1, v16, v4
	v_cvt_pk_bf16_f32 v1, v1, s0
	ds_write_b16 v152, v1 offset:3328
	v_mul_f32_e32 v1, v94, v4
	v_cvt_pk_bf16_f32 v1, v1, s0
	ds_write_b16 v152, v1 offset:3392
	v_mul_f32_e32 v1, v17, v5
	v_cvt_pk_bf16_f32 v1, v1, s0
	ds_write_b16 v152, v1 offset:3456
	v_mul_f32_e32 v1, v95, v5
	v_cvt_pk_bf16_f32 v1, v1, s0
	ds_write_b16 v152, v1 offset:3520
	s_waitcnt lgkmcnt(0)
	v_add_u32_e32 v1, v148, v149
	ds_read_b128 v[2:5], v1
	s_add_i32 s36, s36, 1
	s_cmp_eq_u32 s90, 0x80000
	s_waitcnt lgkmcnt(0)
	global_store_dwordx4 v[8:9], v[2:5], off
	ds_read_b128 v[2:5], v153
	v_add_co_u32_e32 v8, vcc, s2, v6
	s_mov_b32 s2, 0x1d410000
	s_nop 0
	v_addc_co_u32_e32 v9, vcc, 0, v7, vcc
	s_waitcnt lgkmcnt(0)
	global_store_dwordx4 v[8:9], v[2:5], off
	ds_read_b128 v[2:5], v154
	v_add_co_u32_e32 v8, vcc, s2, v6
	s_mov_b32 s2, 0x1d418000
	s_nop 0
	v_addc_co_u32_e32 v9, vcc, 0, v7, vcc
	s_waitcnt lgkmcnt(0)
	global_store_dwordx4 v[8:9], v[2:5], off
	ds_read_b128 v[2:5], v155
	v_add_co_u32_e32 v6, vcc, s2, v6
	s_mov_b64 s[2:3], 0x28000
	s_nop 0
	v_addc_co_u32_e32 v7, vcc, 0, v7, vcc
	v_lshl_add_u64 v[138:139], v[138:139], 0, s[2:3]
	s_waitcnt lgkmcnt(0)
	global_store_dwordx4 v[6:7], v[2:5], off
	s_waitcnt vmcnt(4)
	s_cbranch_scc1 .LBB0_475
; __device__ __forceinline__ float sum_x32(float t) { float a = t, b = t; asm volatile("s_nop 1\n\tv_permlane32_swap_b32 %0, %1" : "+v"(a), "+v"(b)); return a + b; }
; __device__ __forceinline__ unsigned pk2(float lo, float hi) { f32x2_t v = {lo, hi}; bf16x2_t b = __builtin_convertvector(v, bf16x2_t); return __builtin_bit_cast(unsigned, b); }
; __device__ __forceinline__ void attn_phase(int wave_s, LAS unsigned char* lds, const bf16* QKV, bf16* O, const float* qg, const float* kg, const float* sinks, const float* bt) {
;     ...
;             { float s = 0.f;
; #pragma unroll
;                 for (int d0 = 0; d0 < 4; ++d0) {
;                     const float f0 = bflo(qw[d0].x), f1 = bfhi(qw[d0].x), f2 = bflo(qw[d0].y), f3 = bfhi(qw[d0].y), f4 = bflo(qw[d0].z), f5 = bfhi(qw[d0].z), f6 = bflo(qw[d0].w), f7 = bfhi(qw[d0].w);
;                     s += (f0 * f0 + f1 * f1) + (f2 * f2 + f3 * f3) + (f4 * f4 + f5 * f5) + (f6 * f6 + f7 * f7); }
;                 s = sum_x32(s);
;                 const float rs = __builtin_amdgcn_rsqf(s * (1.0f / 64.0f) + EPS) * (0.125f * LOG2E);
; #pragma unroll
;                 for (int d0 = 0; d0 < 4; ++d0) { const f32x4 g0 = *(const f32x4*)(qg + d0 * 16 + hi * 8), g1 = *(const f32x4*)(qg + d0 * 16 + hi * 8 + 4);
;                     v4u o; o.x = pk2(bflo(qw[d0].x) * rs * g0.x, bfhi(qw[d0].x) * rs * g0.y); o.y = pk2(bflo(qw[d0].y) * rs * g0.z, bfhi(qw[d0].y) * rs * g0.w);
;                     o.z = pk2(bflo(qw[d0].z) * rs * g1.x, bfhi(qw[d0].z) * rs * g1.y); o.w = pk2(bflo(qw[d0].w) * rs * g1.z, bfhi(qw[d0].w) * rs * g1.w);
;                     qr[d0] = __builtin_bit_cast(bf16x8, o); } }
;             if (c < 3) {
; #pragma unroll
;                 for (int d0 = 0; d0 < 4; ++d0) qw[d0] = *(const v4u*)(Qb + (size_t)(32 * (c + 1)) * NQKV + d0 * 16); }
.LBB0_499:
	v_and_b32_e32 v53, 0xffff0000, v103
	v_and_b32_e32 v55, 0xffff0000, v102
	v_mov_b32_e32 v54, v53
	v_and_b32_e32 v67, 0xffff0000, v100
	v_pk_mul_f32 v[10:11], v[54:55], v[54:55]
	v_lshlrev_b32_e32 v54, 16, v101
	v_and_b32_e32 v65, 0xffff0000, v101
	v_mov_b32_e32 v64, v67
	v_lshlrev_b32_e32 v52, 16, v102
	v_lshlrev_b32_e32 v56, 16, v100
	v_mov_b32_e32 v57, v54
	v_pk_mul_f32 v[12:13], v[64:65], v[64:65]
	v_lshlrev_b32_e32 v46, 16, v105
	v_lshlrev_b32_e32 v50, 16, v103
	v_mov_b32_e32 v51, v52
	v_pk_fma_f32 v[12:13], v[56:57], v[56:57], v[12:13]
	v_and_b32_e32 v77, 0xffff0000, v96
	v_and_b32_e32 v47, 0xffff0000, v105
	v_mul_f32_e32 v6, v46, v46
	v_pk_fma_f32 v[10:11], v[50:51], v[50:51], v[10:11]
	v_pk_add_f32 v[12:13], v[12:13], v[12:13] op_sel:[0,1] op_sel_hi:[1,0]
	v_and_b32_e32 v71, 0xffff0000, v99
	v_lshlrev_b32_e32 v66, 16, v97
	v_and_b32_e32 v75, 0xffff0000, v97
	v_mov_b32_e32 v74, v77
	v_pk_fma_f32 v[6:7], v[46:47], v[46:47], v[6:7] op_sel_hi:[1,1,0]
	v_lshlrev_b32_e32 v48, 16, v104
	v_pk_add_f32 v[12:13], v[10:11], v[12:13] op_sel:[1,0] op_sel_hi:[0,1]
	v_lshlrev_b32_e32 v64, 16, v98
	v_and_b32_e32 v69, 0xffff0000, v98
	v_mov_b32_e32 v68, v71
	v_lshlrev_b32_e32 v72, 16, v96
	v_mov_b32_e32 v73, v66
	v_pk_mul_f32 v[14:15], v[74:75], v[74:75]
	v_lshlrev_b32_e32 v38, 16, v109
	v_and_b32_e32 v39, 0xffff0000, v109
	v_and_b32_e32 v43, 0xffff0000, v108
	v_and_b32_e32 v49, 0xffff0000, v104
	v_mul_f32_e32 v6, v48, v48
	v_pk_add_f32 v[10:11], v[10:11], v[12:13]
	v_lshlrev_b32_e32 v62, 16, v99
	v_mov_b32_e32 v63, v64
	v_pk_mul_f32 v[12:13], v[68:69], v[68:69]
	v_pk_fma_f32 v[14:15], v[72:73], v[72:73], v[14:15]
	v_and_b32_e32 v1, 0xffff0000, v110
	v_pk_mul_f32 v[4:5], v[38:39], v[38:39]
	v_lshlrev_b32_e32 v44, 16, v106
	v_and_b32_e32 v61, 0xffff0000, v106
	v_pk_fma_f32 v[8:9], v[48:49], v[48:49], v[6:7] op_sel_hi:[1,1,0]
	v_pk_fma_f32 v[12:13], v[62:63], v[62:63], v[12:13]
	v_pk_add_f32 v[14:15], v[14:15], v[14:15] op_sel:[0,1] op_sel_hi:[1,0]
	v_mov_b32_e32 v60, v43
	v_lshlrev_b32_e32 v34, 16, v111
	v_and_b32_e32 v35, 0xffff0000, v111
	v_lshlrev_b32_e32 v40, 16, v108
	v_lshlrev_b32_e32 v42, 16, v107
	v_and_b32_e32 v59, 0xffff0000, v107
	v_pk_add_f32 v[14:15], v[12:13], v[14:15] op_sel:[1,0] op_sel_hi:[0,1]
	v_mov_b32_e32 v58, v1
	v_mov_b32_e32 v41, v44
	v_pk_mul_f32 v[16:17], v[60:61], v[60:61]
	v_mov_b32_e32 v8, v4
	v_mov_b32_e32 v6, v5
	v_pk_mul_f32 v[2:3], v[34:35], v[34:35]
	v_lshlrev_b32_e32 v36, 16, v110
	v_pk_add_f32 v[12:13], v[12:13], v[14:15]
	v_mov_b32_e32 v37, v42
	v_pk_mul_f32 v[14:15], v[58:59], v[58:59]
	v_pk_fma_f32 v[16:17], v[40:41], v[40:41], v[16:17]
	v_pk_add_f32 v[4:5], v[8:9], v[6:7]
	v_pk_fma_f32 v[14:15], v[36:37], v[36:37], v[14:15]
	v_pk_add_f32 v[4:5], v[16:17], v[4:5]
	v_mov_b32_e32 v6, v2
	v_mov_b32_e32 v7, v10
	v_pk_mov_b32 v[2:3], v[2:3], v[12:13] op_sel:[1,0]
	v_pk_add_f32 v[4:5], v[14:15], v[4:5]
	v_pk_add_f32 v[2:3], v[6:7], v[2:3]
	s_cmp_eq_u32 s90, 0x60000
	v_pk_add_f32 v[2:3], v[4:5], v[2:3]
	s_nop 0
	v_add_f32_e32 v58, v2, v3
	v_mov_b32_e32 v60, v58
	s_nop 1
	v_permlane32_swap_b32 v58, v60
	s_cbranch_scc1 .LBB0_501
	global_load_dwordx4 v[96:99], v[138:139], off offset:-64
	global_load_dwordx4 v[100:103], v[138:139], off offset:-32
	global_load_dwordx4 v[104:107], v[138:139], off
	global_load_dwordx4 v[108:111], v[138:139], off offset:32
; #define LAS __attribute__((address_space(3)))
; __device__ __forceinline__ unsigned pk2(float lo, float hi) { f32x2_t v = {lo, hi}; bf16x2_t b = __builtin_convertvector(v, bf16x2_t); return __builtin_bit_cast(unsigned, b); }
; __device__ __forceinline__ void attn_phase(int wave_s, LAS unsigned char* lds, const bf16* QKV, bf16* O, const float* qg, const float* kg, const float* sinks, const float* bt) {
;     ...
;                 const float rs = __builtin_amdgcn_rsqf(s * (1.0f / 64.0f) + EPS) * (0.125f * LOG2E);
; #pragma unroll
;                 for (int d0 = 0; d0 < 4; ++d0) { const f32x4 g0 = *(const f32x4*)(qg + d0 * 16 + hi * 8), g1 = *(const f32x4*)(qg + d0 * 16 + hi * 8 + 4);
;                     v4u o; o.x = pk2(bflo(qw[d0].x) * rs * g0.x, bfhi(qw[d0].x) * rs * g0.y); o.y = pk2(bflo(qw[d0].y) * rs * g0.z, bfhi(qw[d0].y) * rs * g0.w);
;                     o.z = pk2(bflo(qw[d0].z) * rs * g1.x, bfhi(qw[d0].z) * rs * g1.y); o.w = pk2(bflo(qw[d0].w) * rs * g1.z, bfhi(qw[d0].w) * rs * g1.w);
;                     qr[d0] = __builtin_bit_cast(bf16x8, o); } }
;             if (c < 3) {
; #pragma unroll
;                 for (int d0 = 0; d0 < 4; ++d0) qw[d0] = *(const v4u*)(Qb + (size_t)(32 * (c + 1)) * NQKV + d0 * 16); }
;             f32x16 p[5]; float l = 0.f;
; #pragma unroll
;             for (int kk = 0; kk < 5; ++kk) { const bool blk_ok = (nb > 0) || (c + kk >= 4);
;                 if (blk_ok) {
; #pragma unroll
;                     for (int r = 0; r < 16; ++r) p[kk][r] = Bh[160 - 32 * kk - (r & 3) - 8 * (r >> 2)];
; #pragma unroll
;                     for (int d0 = 0; d0 < 4; ++d0) { const bf16x8 kf = *(const LAS bf16x8*)(Ks + ((c + kk) * 32 + r32) * KS_STRIDE + d0 * 16 + hi * 8);
;                         p[kk] = __builtin_amdgcn_mfma_f32_32x32x16_bf16(kf, qr[d0], p[kk], 0, 0, 0); }
.LBB0_501:
	v_mov_b32_e32 v37, v1
	v_add_f32_e32 v1, v58, v60
	v_fmamk_f32 v1, v1, 0x3c800000, v250
	v_rsq_f32_e32 v1, v1
	v_mov_b32_e32 v73, v77
	v_mov_b32_e32 v45, v61
	v_mov_b32_e32 v57, v67
	v_mul_f32_e32 v58, 0x3e38aa3b, v1
	v_pk_mul_f32 v[60:61], v[58:59], v[72:73] op_sel_hi:[0,1]
	v_mov_b32_e32 v67, v75
	v_pk_mul_f32 v[30:31], v[168:169], v[60:61]
	v_mov_b32_e32 v51, v53
	v_cvt_pk_bf16_f32 v112, v30, v31
	v_pk_mul_f32 v[30:31], v[58:59], v[66:67] op_sel_hi:[0,1]
	v_mov_b32_e32 v53, v55
	v_mov_b32_e32 v55, v65
	v_mov_b32_e32 v65, v69
	v_pk_mul_f32 v[30:31], v[170:171], v[30:31]
	v_mov_b32_e32 v63, v71
	v_cvt_pk_bf16_f32 v113, v30, v31
	v_pk_mul_f32 v[30:31], v[58:59], v[64:65] op_sel_hi:[0,1]
	v_pk_mul_f32 v[26:27], v[164:165], v[30:31]
	v_mov_b32_e32 v41, v43
	v_cvt_pk_bf16_f32 v114, v26, v27
	v_pk_mul_f32 v[26:27], v[58:59], v[62:63] op_sel_hi:[0,1]
	v_pk_mul_f32 v[26:27], v[166:167], v[26:27]
	v_mov_b32_e32 v43, v59
	v_cvt_pk_bf16_f32 v115, v26, v27
	v_pk_mul_f32 v[26:27], v[58:59], v[56:57] op_sel_hi:[0,1]
	v_pk_mul_f32 v[22:23], v[176:177], v[26:27]
	v_cndmask_b32_e64 v1, 0, 1, s[88:89]
	v_cvt_pk_bf16_f32 v116, v22, v23
	v_pk_mul_f32 v[22:23], v[58:59], v[54:55] op_sel_hi:[0,1]
	v_pk_mul_f32 v[22:23], v[178:179], v[22:23]
	v_cmp_ne_u32_e64 s[6:7], 1, v1
	v_cvt_pk_bf16_f32 v117, v22, v23
	v_pk_mul_f32 v[22:23], v[58:59], v[52:53] op_sel_hi:[0,1]
	v_pk_mul_f32 v[18:19], v[172:173], v[22:23]
	s_andn2_b64 vcc, exec, s[88:89]
	v_cvt_pk_bf16_f32 v118, v18, v19
	v_pk_mul_f32 v[18:19], v[58:59], v[50:51] op_sel_hi:[0,1]
	v_pk_mul_f32 v[18:19], v[174:175], v[18:19]
	s_nop 0
	v_cvt_pk_bf16_f32 v119, v18, v19
	v_pk_mul_f32 v[18:19], v[58:59], v[48:49] op_sel_hi:[0,1]
	v_pk_mul_f32 v[14:15], v[184:185], v[18:19]
	s_nop 0
	v_cvt_pk_bf16_f32 v120, v14, v15
	v_pk_mul_f32 v[14:15], v[58:59], v[46:47] op_sel_hi:[0,1]
	v_pk_mul_f32 v[14:15], v[186:187], v[14:15]
	s_nop 0
	v_cvt_pk_bf16_f32 v121, v14, v15
	v_pk_mul_f32 v[14:15], v[58:59], v[44:45] op_sel_hi:[0,1]
	v_pk_mul_f32 v[10:11], v[180:181], v[14:15]
	s_nop 0
	v_cvt_pk_bf16_f32 v122, v10, v11
	v_pk_mul_f32 v[10:11], v[58:59], v[42:43] op_sel_hi:[0,1]
	v_pk_mul_f32 v[10:11], v[182:183], v[10:11]
	s_nop 0
	v_cvt_pk_bf16_f32 v123, v10, v11
	v_pk_mul_f32 v[10:11], v[58:59], v[40:41] op_sel_hi:[0,1]
	v_pk_mul_f32 v[6:7], v[10:11], v[192:193]
	s_nop 0
	v_cvt_pk_bf16_f32 v124, v6, v7
	v_pk_mul_f32 v[6:7], v[58:59], v[38:39] op_sel_hi:[0,1]
	v_pk_mul_f32 v[6:7], v[6:7], v[194:195]
	s_nop 0
	v_cvt_pk_bf16_f32 v125, v6, v7
	v_pk_mul_f32 v[6:7], v[58:59], v[36:37] op_sel_hi:[0,1]
	v_pk_mul_f32 v[2:3], v[6:7], v[188:189]
	s_nop 0
	v_cvt_pk_bf16_f32 v126, v2, v3
	v_pk_mul_f32 v[2:3], v[58:59], v[34:35] op_sel_hi:[0,1]
	v_pk_mul_f32 v[2:3], v[2:3], v[190:191]
	s_nop 0
	v_cvt_pk_bf16_f32 v127, v2, v3
	s_cbranch_vccnz .LBB0_503
	ds_read2_b32 v[2:3], v145 offset0:159 offset1:160
	ds_read2_b32 v[4:5], v145 offset0:157 offset1:158
	ds_read2_b32 v[6:7], v145 offset0:151 offset1:152
	ds_read2_b32 v[8:9], v145 offset0:149 offset1:150
	ds_read2_b32 v[10:11], v145 offset0:143 offset1:144
	ds_read2_b32 v[12:13], v145 offset0:141 offset1:142
	ds_read2_b32 v[14:15], v145 offset0:135 offset1:136
	ds_read2_b32 v[32:33], v145 offset0:133 offset1:134
	s_waitcnt lgkmcnt(7)
	v_mov_b32_e32 v16, v3
	v_mov_b32_e32 v17, v2
	s_waitcnt lgkmcnt(6)
	v_mov_b32_e32 v18, v5
	v_mov_b32_e32 v19, v4
	ds_read_b128 v[2:5], v157
	s_waitcnt lgkmcnt(6)
	v_mov_b32_e32 v20, v7
	v_mov_b32_e32 v21, v6
	s_waitcnt lgkmcnt(5)
	v_mov_b32_e32 v22, v9
	v_mov_b32_e32 v23, v8
	s_waitcnt lgkmcnt(4)
	v_mov_b32_e32 v24, v11
	v_mov_b32_e32 v25, v10
	s_waitcnt lgkmcnt(3)
	v_mov_b32_e32 v26, v13
	v_mov_b32_e32 v27, v12
	s_waitcnt lgkmcnt(2)
	v_mov_b32_e32 v28, v15
	v_mov_b32_e32 v29, v14
	s_waitcnt lgkmcnt(1)
	v_mov_b32_e32 v30, v33
	v_mov_b32_e32 v31, v32
	s_waitcnt lgkmcnt(0)
	s_nop 0
	v_mfma_f32_32x32x16_bf16 v[16:31], v[2:5], v[112:115], v[16:31]
	ds_read_b128 v[2:5], v157 offset:32
	s_waitcnt lgkmcnt(0)
	v_mfma_f32_32x32x16_bf16 v[16:31], v[2:5], v[116:119], v[16:31]
	ds_read_b128 v[2:5], v157 offset:64
	s_waitcnt lgkmcnt(0)
	v_mfma_f32_32x32x16_bf16 v[16:31], v[2:5], v[120:123], v[16:31]
	ds_read_b128 v[2:5], v157 offset:96
	s_waitcnt lgkmcnt(0)
	v_mfma_f32_32x32x16_bf16 v[16:31], v[2:5], v[124:127], v[16:31]
	s_branch .LBB0_504
